# swa_attn unit prologue: the 8 K/V staging loads issued back to back with distinct destinations and counted waits (on top of the LayerNorm edit)
# baseline (speedup 1.0000x reference)
_Z4mega4Args:
	s_mov_b64 s[96:97], s[0:1]
	s_mov_b32 s100, 0
	s_mov_b32 s91, s2
	s_load_dwordx4 s[0:3], s[96:97], 0x110
	s_load_dword s94, s[96:97], 0x128
	v_lshl_add_u32 v2, v0, 2, 0
	v_or_b32_e32 v1, 0xfffffe00, v0
	v_add_u32_e32 v2, 0x25000, v2
	s_waitcnt lgkmcnt(0)
	v_writelane_b32 v250, s0, 0
	s_mov_b64 s[4:5], 0
	v_mov_b32_e32 v3, 0
	v_writelane_b32 v250, s1, 1
	v_writelane_b32 v250, s2, 2
	v_writelane_b32 v250, s3, 3
	s_add_u32 s0, s96, 0x128
	s_addc_u32 s1, s97, 0
	v_writelane_b32 v250, s0, 4
	s_nop 1
	v_writelane_b32 v250, s1, 5
	v_readfirstlane_b32 s1, v0

.Lmy_reentry:
	s_load_dwordx4 s[4:7], s[96:97], 0x110
	s_waitcnt lgkmcnt(0)
	s_cmp_eq_u32 s100, 0
	s_cbranch_scc1 .Lmy_noprobe
	s_mov_b32 s6, 47
	s_mov_b32 s7, 49
	s_cmp_eq_u32 s100, 1
	s_cbranch_scc1 .Lmy_setrange
	s_mov_b32 s6, 34
	s_mov_b32 s7, 35
.Lmy_setrange:
	s_nop 0
	v_writelane_b32 v250, s6, 2
	v_writelane_b32 v250, s7, 3
.Lmy_noprobe:
	s_cmp_lt_i32 s6, 1
	s_cselect_b64 s[2:3], -1, 0
	s_cmp_gt_i32 s7, 0
	s_cselect_b64 s[4:5], -1, 0
	s_and_b64 s[2:3], s[2:3], s[4:5]
	s_and_b64 vcc, exec, s[2:3]
	s_cbranch_vccnz .LBB0_7
	s_lshl_b32 s2, s91, 9
	v_writelane_b32 v250, s2, 6
	s_lshl_b32 s78, s94, 9
	s_mov_b64 s[4:5], 0
	s_branch .LBB0_8

.LBB0_53:
	s_add_i32 s10, s10, 1
	v_readlane_b32 s2, v253, 8
	v_readlane_b32 s3, v253, 9
	s_add_u32 s2, s2, 0x1000000
	s_addc_u32 s3, s3, 0
	v_writelane_b32 v253, s2, 8
	s_cmp_eq_u32 s10, 4
	s_nop 0
	v_writelane_b32 v253, s3, 9
	s_cbranch_scc0 .LBB0_54
	s_cmp_ge_u32 s100, 3
	s_cbranch_scc1 .Lmy_exit
	s_add_u32 s100, s100, 1
	v_readlane_b32 s91, v250, 7
	v_readlane_b32 s1, v250, 8
	s_load_dword s94, s[96:97], 0x128
	s_load_dwordx2 s[14:15], s[96:97], 0x110
	s_getreg_b32 s0, hwreg(HW_REG_XCC_ID, 0, 4)
	s_and_b32 s0, s0, 15
	s_nop 3
	s_lshl_b32 s1, s1, 6
	s_waitcnt lgkmcnt(0)
	s_add_u32 s14, s14, 0x4000
	s_addc_u32 s15, s15, 0
	s_branch .Lmy_reentry
.Lmy_exit:
	s_getpc_b64 s[98:99]
